# adds: copy-filler chunk-claim atomic left in flight while the chunk streams (read at the next loop top)
# speedup vs baseline: 1.0035x; 1.0035x over previous
.LBB0_982:
	s_or_b64 exec, exec, s[12:13]
	s_waitcnt vmcnt(0)
	v_readfirstlane_b32 s0, v1
	s_nop 1
	v_add_u32_e32 v65, s0, v0
	v_mov_b32_e32 v253, v65

.LBB0_984:
.LBB0_985:
	s_and_saveexec_b64 s[16:17], s[70:71]
	s_cbranch_execz .LBB0_987
	s_waitcnt vmcnt(7)
	v_mov_b32_e32 v65, v253
	v_cmp_gt_u32_e32 vcc, s0, v65
	v_mov_b32_e32 v1, s1
	s_nop 0
	v_cndmask_b32_e32 v0, -1, v65, vcc
	ds_write_b32 v1, v0
.LBB0_987:
	s_or_b64 exec, exec, s[16:17]
	s_waitcnt lgkmcnt(0)
	s_barrier
	s_waitcnt vmcnt(7)
	ds_read_b32 v0, v64
	s_waitcnt lgkmcnt(0)
	s_barrier
	s_waitcnt lgkmcnt(0)
	v_cmp_gt_i32_e32 vcc, 0, v0
	v_readfirstlane_b32 s37, v0
	s_cbranch_vccnz .LBB0_1005
	s_and_saveexec_b64 s[16:17], s[70:71]
	s_cbranch_execz .LBB0_994
	v_cmp_gt_u32_e32 vcc, s2, v66
	v_mov_b32_e32 v65, 0x1500
	v_mov_b32_e32 v253, 0x1500
	s_and_saveexec_b64 s[18:19], vcc
	s_cbranch_execz .LBB0_993
	s_mov_b64 s[22:23], exec
	v_mbcnt_lo_u32_b32 v0, s22, 0
	v_mbcnt_hi_u32_b32 v0, s23, v0
	v_cmp_eq_u32_e32 vcc, 0, v0
	s_and_saveexec_b64 s[20:21], vcc
	s_cbranch_execz .LBB0_992
	s_bcnt1_i32_b64 s12, s[22:23]
	v_mov_b32_e32 v1, s12
	global_atomic_add v253, v61, v1, s[6:7] sc0
.LBB0_992:
	s_or_b64 exec, exec, s[20:21]
	global_load_dword v66, v61, s[4:5] sc1
.LBB0_993:
	s_or_b64 exec, exec, s[18:19]

.LBB0_1192:
	s_or_b64 exec, exec, s[16:17]
	s_waitcnt lgkmcnt(0)
	s_barrier
	s_waitcnt vmcnt(7)
	ds_read_b32 v0, v64
	s_waitcnt lgkmcnt(0)
	s_barrier
	s_waitcnt lgkmcnt(0)
	v_cmp_gt_i32_e32 vcc, 0, v0
	v_readfirstlane_b32 s35, v0
	s_cbranch_vccnz .LBB0_1208
	s_and_saveexec_b64 s[16:17], s[70:71]
	s_cbranch_execz .LBB0_1197
	s_mov_b64 s[20:21], exec
	v_mbcnt_lo_u32_b32 v0, s20, 0
	v_mbcnt_hi_u32_b32 v0, s21, v0
	v_cmp_eq_u32_e32 vcc, 0, v0
	s_and_saveexec_b64 s[18:19], vcc
	s_cbranch_execz .LBB0_1196
	s_bcnt1_i32_b64 s12, s[20:21]
	v_mov_b32_e32 v1, s12
	global_atomic_add v253, v61, v1, s[6:7] sc0
.LBB0_1196:
	s_or_b64 exec, exec, s[18:19]
	global_load_dword v2, v61, s[4:5] sc1
.LBB0_1197:
	s_or_b64 exec, exec, s[16:17]
	s_cmpk_lt_u32 s35, 0x100
	s_cselect_b64 s[16:17], -1, 0
	s_cmpk_gt_u32 s35, 0xff
	s_mov_b64 s[20:21], -1
	s_cbranch_scc0 .LBB0_1202
	s_cmpk_gt_u32 s35, 0x4ff
	s_mov_b64 s[18:19], -1
	s_cbranch_scc0 .LBB0_1200
	s_add_i32 s12, s35, 0xfffffb00
	s_lshr_b32 s12, s12, 5
	s_mov_b64 s[18:19], 0
